# mLSTM-prep QK^T: all operand fragments of two k-slices are read up front with counted waits; the per-wave triangular MFMA work then runs without an LDS round trip per MFMA
# speedup vs baseline: 1.0029x; 1.0029x over previous
.LBB0_637:
	s_or_b64 exec, exec, s[38:39]
	ds_read_b128 v[176:179], v136
	ds_read_b128 v[180:183], v137 offset:13312
	ds_read_b128 v[184:187], v137 offset:16640
	ds_read_b128 v[188:191], v137 offset:19968
	ds_read_b128 v[192:195], v137 offset:23296
	ds_read_b128 v[196:199], v136 offset:64
	ds_read_b128 v[200:203], v137 offset:13376
	ds_read_b128 v[244:247], v137 offset:16704
	ds_read_b128 v[248:251], v137 offset:20032
	ds_read_b128 v[80:83], v137 offset:23360
	s_mov_b32 s82, s77
	s_mov_b32 s83, s77
	s_mov_b32 s80, s77
	s_mov_b32 s81, s77
	v_mov_b64_e32 v[90:91], s[82:83]
	s_xor_b64 s[96:97], s[70:71], -1
	v_mov_b64_e32 v[88:89], s[80:81]
	v_mov_b32_e32 v2, v1
	v_mov_b32_e32 v3, v1
	v_mov_b32_e32 v0, v1
	v_mov_b64_e32 v[86:87], v[2:3]
	v_mov_b64_e32 v[84:85], v[0:1]
	v_mov_b64_e32 v[78:79], v[2:3]
	v_mov_b64_e32 v[76:77], v[0:1]
	s_waitcnt lgkmcnt(8)
	v_mfma_f32_16x16x32_bf16 v[92:95], v[176:179], v[180:183], 0
	s_and_b64 vcc, exec, s[40:41]
	s_cbranch_vccz .Lqkm_a
	s_waitcnt lgkmcnt(7)
	v_mfma_f32_16x16x32_bf16 v[88:91], v[176:179], v[184:187], 0
	s_and_b64 vcc, exec, s[24:25]
	s_cbranch_vccz .Lqkm_a
	s_waitcnt lgkmcnt(6)
	v_mfma_f32_16x16x32_bf16 v[84:87], v[176:179], v[188:191], 0
	s_and_b64 vcc, exec, s[58:59]
	s_cbranch_vccz .Lqkm_a
	s_waitcnt lgkmcnt(5)
	v_mfma_f32_16x16x32_bf16 v[76:79], v[176:179], v[192:195], 0
.Lqkm_a:
	ds_read_b128 v[176:179], v136 offset:128
	ds_read_b128 v[180:183], v137 offset:13440
	ds_read_b128 v[184:187], v137 offset:16768
	ds_read_b128 v[188:191], v137 offset:20096
	ds_read_b128 v[192:195], v137 offset:23424
	s_waitcnt lgkmcnt(8)
	v_mfma_f32_16x16x32_bf16 v[92:95], v[196:199], v[200:203], v[92:95]
	s_and_b64 vcc, exec, s[40:41]
	s_cbranch_vccz .Lqkm_b
	s_waitcnt lgkmcnt(7)
	v_mfma_f32_16x16x32_bf16 v[88:91], v[196:199], v[244:247], v[88:91]
	s_and_b64 vcc, exec, s[24:25]
	s_cbranch_vccz .Lqkm_b
	s_waitcnt lgkmcnt(6)
	v_mfma_f32_16x16x32_bf16 v[84:87], v[196:199], v[248:251], v[84:87]
	s_and_b64 vcc, exec, s[58:59]
	s_cbranch_vccz .Lqkm_b
	s_waitcnt lgkmcnt(5)
	v_mfma_f32_16x16x32_bf16 v[76:79], v[196:199], v[80:83], v[76:79]
.Lqkm_b:
	s_waitcnt lgkmcnt(3)
	v_mfma_f32_16x16x32_bf16 v[92:95], v[176:179], v[180:183], v[92:95]
	s_and_b64 vcc, exec, s[40:41]
	s_cbranch_vccz .Lqkm_c
	s_waitcnt lgkmcnt(2)
	v_mfma_f32_16x16x32_bf16 v[88:91], v[176:179], v[184:187], v[88:91]
	s_and_b64 vcc, exec, s[24:25]
	s_cbranch_vccz .Lqkm_c
	s_waitcnt lgkmcnt(1)
	v_mfma_f32_16x16x32_bf16 v[84:87], v[176:179], v[188:191], v[84:87]
	s_and_b64 vcc, exec, s[58:59]
	s_cbranch_vccz .Lqkm_c
	s_waitcnt lgkmcnt(0)
	v_mfma_f32_16x16x32_bf16 v[76:79], v[176:179], v[192:195], v[76:79]
.Lqkm_c:
.LBB0_651:
	s_or_b64 exec, exec, s[38:39]
	v_add_u32_e32 v96, 0xc000, v142
	ds_read_b128 v[80:83], v138 offset:49408
	ds_read2_b32 v[2:3], v96 offset1:16
	s_waitcnt lgkmcnt(0)
	v_sub_f32_e32 v0, v2, v80
	v_mul_f32_e32 v0, 0x3fb8aa3b, v0
	v_exp_f32_e32 v0, v0
	s_nop 0
	v_mul_f32_e32 v0, v92, v0
	v_cndmask_b32_e64 v0, v0, 0, s[60:61]
	v_add_f32_e32 v97, 0, v0
	v_cvt_pk_bf16_f32 v0, v0, s0
	ds_write_b16 v143, v0 offset:39936
	v_sub_f32_e32 v0, v2, v81
	v_mul_f32_e32 v0, 0x3fb8aa3b, v0
	v_exp_f32_e32 v0, v0
	s_nop 0
	v_mul_f32_e32 v0, v93, v0
	v_cndmask_b32_e64 v0, v0, 0, s[62:63]
	v_cvt_pk_bf16_f32 v92, v0, s0
	ds_write_b16 v144, v92 offset:39936
	v_sub_f32_e32 v92, v2, v82
	v_mul_f32_e32 v92, 0x3fb8aa3b, v92
	v_exp_f32_e32 v92, v92
	v_sub_f32_e32 v2, v2, v83
	v_mul_f32_e32 v2, 0x3fb8aa3b, v2
	v_exp_f32_e32 v2, v2
	v_mul_f32_e32 v92, v94, v92
	v_cndmask_b32_e64 v92, v92, 0, s[64:65]
	v_cvt_pk_bf16_f32 v93, v92, s0
	v_mul_f32_e32 v2, v95, v2
	ds_write_b16 v145, v93 offset:39936
	v_cndmask_b32_e64 v93, v2, 0, s[66:67]
	v_cvt_pk_bf16_f32 v2, v93, s0
	ds_write_b16 v146, v2 offset:39936
	v_sub_f32_e32 v2, v3, v80
	v_mul_f32_e32 v2, 0x3fb8aa3b, v2
	v_exp_f32_e32 v2, v2
	s_nop 0
	v_mul_f32_e32 v2, v88, v2
	v_cndmask_b32_e64 v2, v2, 0, s[26:27]
	v_add_f32_e32 v94, v97, v2
	v_cvt_pk_bf16_f32 v2, v2, s0
	ds_write_b16 v147, v2 offset:39968
	v_sub_f32_e32 v2, v3, v81
	v_mul_f32_e32 v2, 0x3fb8aa3b, v2
	v_exp_f32_e32 v2, v2
	s_nop 0
	v_mul_f32_e32 v2, v89, v2
	v_cndmask_b32_e64 v89, v2, 0, s[28:29]
	v_cvt_pk_bf16_f32 v2, v89, s0
	ds_write_b16 v148, v2 offset:39968
	v_sub_f32_e32 v2, v3, v82
	v_mul_f32_e32 v2, 0x3fb8aa3b, v2
	v_exp_f32_e32 v2, v2
	s_nop 0
	v_mul_f32_e32 v2, v90, v2
	v_cndmask_b32_e64 v90, v2, 0, s[78:79]
	v_cvt_pk_bf16_f32 v2, v90, s0
	ds_write_b16 v149, v2 offset:39968
	v_sub_f32_e32 v2, v3, v83
	v_mul_f32_e32 v2, 0x3fb8aa3b, v2
	v_exp_f32_e32 v2, v2
	s_nop 0
	v_mul_f32_e32 v2, v91, v2
	v_cndmask_b32_e64 v88, v2, 0, s[84:85]
	v_cvt_pk_bf16_f32 v2, v88, s0
	ds_write_b16 v159, v2 offset:39968
	ds_read2_b32 v[2:3], v96 offset0:32 offset1:48
	s_waitcnt lgkmcnt(0)
	v_sub_f32_e32 v91, v2, v80
	v_mul_f32_e32 v91, 0x3fb8aa3b, v91
	v_exp_f32_e32 v91, v91
	s_nop 0
	v_mul_f32_e32 v84, v84, v91
	v_cndmask_b32_e64 v84, v84, 0, s[92:93]
	v_add_f32_e32 v91, v94, v84
	v_cvt_pk_bf16_f32 v84, v84, s0
	ds_write_b16 v147, v84 offset:40000
	v_sub_f32_e32 v84, v2, v81
	v_mul_f32_e32 v84, 0x3fb8aa3b, v84
	v_exp_f32_e32 v84, v84
	s_nop 0
	v_mul_f32_e32 v84, v85, v84
	v_cndmask_b32_e64 v84, v84, 0, s[72:73]
	v_cvt_pk_bf16_f32 v85, v84, s0
	ds_write_b16 v148, v85 offset:40000
	v_sub_f32_e32 v85, v2, v82
	v_mul_f32_e32 v85, 0x3fb8aa3b, v85
	v_exp_f32_e32 v85, v85
	v_sub_f32_e32 v2, v2, v83
	v_mul_f32_e32 v2, 0x3fb8aa3b, v2
	v_exp_f32_e32 v2, v2
	v_mul_f32_e32 v85, v86, v85
	v_cndmask_b32_e64 v85, v85, 0, s[14:15]
	v_cvt_pk_bf16_f32 v86, v85, s0
	v_mul_f32_e32 v2, v87, v2
	ds_write_b16 v149, v86 offset:40000
	v_cndmask_b32_e64 v86, v2, 0, s[34:35]
	v_cvt_pk_bf16_f32 v2, v86, s0
	ds_write_b16 v159, v2 offset:40000
	v_sub_f32_e32 v2, v3, v80
	v_mul_f32_e32 v2, 0x3fb8aa3b, v2
	v_exp_f32_e32 v2, v2
	s_nop 0
	v_mul_f32_e32 v2, v76, v2
	v_cndmask_b32_e64 v2, v2, 0, s[8:9]
	v_add_f32_e32 v87, v91, v2
	v_cvt_pk_bf16_f32 v2, v2, s0
	ds_write_b16 v147, v2 offset:40032
	v_sub_f32_e32 v2, v3, v81
	v_mul_f32_e32 v2, 0x3fb8aa3b, v2
	v_exp_f32_e32 v2, v2
	s_nop 0
	v_mul_f32_e32 v2, v77, v2
	v_cndmask_b32_e64 v76, v2, 0, s[10:11]
	v_cvt_pk_bf16_f32 v2, v76, s0
	ds_write_b16 v148, v2 offset:40032
	v_sub_f32_e32 v2, v3, v82
	v_mul_f32_e32 v2, 0x3fb8aa3b, v2
	v_exp_f32_e32 v2, v2
	s_nop 0
	v_mul_f32_e32 v2, v78, v2
	v_cndmask_b32_e64 v77, v2, 0, s[18:19]
	v_cvt_pk_bf16_f32 v2, v77, s0
	ds_write_b16 v149, v2 offset:40032
	v_sub_f32_e32 v2, v3, v83
	v_mul_f32_e32 v2, 0x3fb8aa3b, v2
	v_exp_f32_e32 v2, v2
	v_and_b32_e32 v3, 64, v209
	v_add_u32_e32 v3, 64, v3
	v_mul_f32_e32 v2, v79, v2
	v_cndmask_b32_e64 v78, v2, 0, s[94:95]
	v_cvt_pk_bf16_f32 v2, v78, s0
	ds_write_b16 v159, v2 offset:40032
	v_xor_b32_e32 v2, 1, v209
	v_cmp_lt_i32_e32 vcc, v2, v3
	s_nop 1
	v_cndmask_b32_e32 v2, v209, v2, vcc
	v_lshlrev_b32_e32 v79, 2, v2
	s_nop 1
	v_mov_b32_dpp v83, v87 quad_perm:[1,0,3,2] row_mask:0xf bank_mask:0xf
	v_xor_b32_e32 v2, 2, v209
	v_cmp_lt_i32_e32 vcc, v2, v3
	s_waitcnt lgkmcnt(0)
	v_add_f32_e32 v83, v87, v83
	v_cndmask_b32_e32 v2, v209, v2, vcc
	v_lshlrev_b32_e32 v80, 2, v2
	s_nop 1
	v_mov_b32_dpp v87, v83 quad_perm:[2,3,0,1] row_mask:0xf bank_mask:0xf
	v_xor_b32_e32 v2, 4, v209
	v_cmp_lt_i32_e32 vcc, v2, v3
	s_waitcnt lgkmcnt(0)
	v_add_f32_e32 v83, v83, v87
	v_cndmask_b32_e32 v2, v209, v2, vcc
	v_lshlrev_b32_e32 v81, 2, v2
	s_nop 1
	v_mov_b32_dpp v87, v83 quad_perm:[3,2,1,0] row_mask:0xf bank_mask:0xf
	s_nop 1
	v_mov_b32_dpp v87, v87 row_half_mirror row_mask:0xf bank_mask:0xf
	v_xor_b32_e32 v2, 8, v209
	v_cmp_lt_i32_e32 vcc, v2, v3
	s_waitcnt lgkmcnt(0)
	v_add_f32_e32 v83, v83, v87
	v_cndmask_b32_e32 v2, v209, v2, vcc
	v_lshlrev_b32_e32 v82, 2, v2
	s_nop 1
	v_mov_b32_dpp v87, v83 row_ror:8 row_mask:0xf bank_mask:0xf
	v_lshl_add_u64 v[2:3], s[76:77], 4, v[118:119]
	s_and_saveexec_b64 s[38:39], s[68:69]
	s_cbranch_execz .LBB0_653
	s_waitcnt lgkmcnt(0)
	v_add_f32_e32 v83, v83, v87
	v_cndmask_b32_e64 v87, v160, v127, s[70:71]
	v_or_b32_e32 v94, v87, v171
	v_ashrrev_i32_e32 v95, 31, v94
	v_lshlrev_b64 v[94:95], 5, v[94:95]
	v_lshl_add_u64 v[94:95], v[2:3], 0, v[94:95]
	global_store_dword v[94:95], v83, off

.LBB0_657:
	s_or_b64 exec, exec, s[38:39]
	v_add_f32_e32 v0, 0, v93
	v_add_f32_e32 v0, v0, v88
	v_add_f32_e32 v0, v0, v86
	v_add_f32_e32 v0, v0, v78
	s_waitcnt lgkmcnt(0)
	s_nop 1
	v_mov_b32_dpp v76, v0 quad_perm:[1,0,3,2] row_mask:0xf bank_mask:0xf
	s_waitcnt lgkmcnt(0)
	v_add_f32_e32 v0, v0, v76
	s_nop 1
	v_mov_b32_dpp v76, v0 quad_perm:[2,3,0,1] row_mask:0xf bank_mask:0xf
	s_waitcnt lgkmcnt(0)
	v_add_f32_e32 v0, v0, v76
	s_nop 1
	v_mov_b32_dpp v76, v0 quad_perm:[3,2,1,0] row_mask:0xf bank_mask:0xf
	s_nop 1
	v_mov_b32_dpp v76, v76 row_half_mirror row_mask:0xf bank_mask:0xf
	s_waitcnt lgkmcnt(0)
	v_add_f32_e32 v0, v0, v76
	s_nop 1
	v_mov_b32_dpp v76, v0 row_ror:8 row_mask:0xf bank_mask:0xf
	s_and_saveexec_b64 s[38:39], s[68:69]
	s_cbranch_execz .LBB0_629
	s_waitcnt lgkmcnt(0)
	v_add_f32_e32 v0, v0, v76
	v_cndmask_b32_e64 v76, v163, v141, s[70:71]
	v_or_b32_e32 v76, v76, v171
	v_ashrrev_i32_e32 v77, 31, v76
	v_lshlrev_b64 v[76:77], 5, v[76:77]
	v_lshl_add_u64 v[2:3], v[2:3], 0, v[76:77]
	global_store_dword v[2:3], v0, off
	s_branch .LBB0_629
.LBB0_663:
	v_readlane_b32 s56, v255, 8
	v_readlane_b32 s88, v254, 63
	v_readlane_b32 s84, v255, 10
	v_readlane_b32 s80, v255, 1
	v_readlane_b32 s82, v255, 16
	v_readlane_b32 s54, v255, 3
	v_readlane_b32 s57, v255, 9
	s_mov_b64 s[2:3], 0
	v_readlane_b32 s89, v255, 0
	v_readlane_b32 s85, v255, 11
	v_readlane_b32 s86, v255, 12
	v_readlane_b32 s87, v255, 13
	v_readlane_b32 s81, v255, 2
	v_readlane_b32 s83, v255, 17
	s_movk_i32 s68, 0x3ff
	s_mov_b32 s69, 0x10000
	s_movk_i32 s70, 0x7fff
	s_movk_i32 s71, 0xb00
	s_movk_i32 s90, 0xc0
	s_mov_b32 s73, 0xb000
	s_movk_i32 s78, 0x80
	s_mov_b32 s79, 0x40000
	s_mov_b32 s91, 0x48000
	s_mov_b32 s92, 0x50000
	s_mov_b32 s93, 0xba2e8ba3
	s_mov_b32 s94, 0x2e8ba2e8
	s_mov_b32 s95, 0x3fb8aa3b
	s_mov_b32 s63, 0x78787879
	s_mov_b32 s64, 0xc2ce8ed0
	s_mov_b32 s65, 0x42b17218
	s_movk_i32 s58, 0x15ff
	s_movk_i32 s27, 0x5ff
	v_readlane_b32 s28, v254, 62
	v_readlane_b32 s55, v255, 4
	s_mov_b32 s57, s31
	v_readlane_b32 s44, v255, 5
	v_readlane_b32 s45, v255, 6
